# noprio + rstd rows of each unit via early LDS-DMA in both P1 and P7 epilogues
# speedup vs baseline: 1.0167x; 1.0021x over previous
.LBB0_751:
	v_lshlrev_b32_e32 v2, 4, v0
	s_lshl_b32 s100, s16, 14
	s_add_u32 s100, s50, s100
	s_addc_u32 s101, s51, 0
	v_readfirstlane_b32 s57, v2
	s_nop 3
	s_add_i32 m0, s57, 0x20400
	s_nop 0
	global_load_lds_dwordx4 v2, s[100:101]
	v_add_u32_e32 v2, 0x2000, v2
	s_add_i32 m0, s57, 0x22400
	s_nop 0
	global_load_lds_dwordx4 v2, s[100:101]
	s_ashr_i32 s57, s56, 31
	s_lshl_b64 s[22:23], s[56:57], 19
	s_add_u32 s58, s28, s22
	s_addc_u32 s59, s29, s23
	s_and_b64 s[22:23], s[38:39], exec
	s_cselect_b32 s15, s59, s19
	s_cselect_b32 s17, s58, s18
	s_ashr_i32 s55, s54, 31
	s_lshl_b64 s[22:23], s[54:55], 19
	s_add_u32 s60, s30, s22
	s_addc_u32 s61, s31, s23
	s_and_b64 s[22:23], s[38:39], exec
	s_cselect_b32 s24, s61, s21
	s_cselect_b32 s25, s60, s20
	s_add_u32 s18, s18, 0x40080
	s_addc_u32 s19, s19, 0
	s_add_u32 s26, s20, 0x100
	v_mov_b32_e32 v12, 0
	s_addc_u32 s27, s21, 0
	s_mov_b32 s40, -2
	v_mov_b32_e32 v13, v12
	v_mov_b32_e32 v14, v12
	v_mov_b32_e32 v15, v12
	v_mov_b32_e32 v16, v12
	v_mov_b32_e32 v17, v12
	v_mov_b32_e32 v18, v12
	v_mov_b32_e32 v19, v12
	v_mov_b32_e32 v28, v12
	v_mov_b32_e32 v29, v12
	v_mov_b32_e32 v30, v12
	v_mov_b32_e32 v31, v12
	v_mov_b32_e32 v32, v12
	v_mov_b32_e32 v33, v12
	v_mov_b32_e32 v34, v12
	v_mov_b32_e32 v35, v12
	v_mov_b32_e32 v44, v12
	v_mov_b32_e32 v45, v12
	v_mov_b32_e32 v46, v12
	v_mov_b32_e32 v47, v12
	v_mov_b32_e32 v48, v12
	v_mov_b32_e32 v49, v12
	v_mov_b32_e32 v50, v12
	v_mov_b32_e32 v51, v12
	v_mov_b32_e32 v60, v12
	v_mov_b32_e32 v61, v12
	v_mov_b32_e32 v62, v12
	v_mov_b32_e32 v63, v12
	v_mov_b32_e32 v64, v12
	v_mov_b32_e32 v65, v12
	v_mov_b32_e32 v66, v12
	v_mov_b32_e32 v67, v12
	v_mov_b32_e32 v4, v12
	v_mov_b32_e32 v5, v12
	v_mov_b32_e32 v6, v12
	v_mov_b32_e32 v7, v12
	v_mov_b32_e32 v8, v12
	v_mov_b32_e32 v9, v12
	v_mov_b32_e32 v10, v12
	v_mov_b32_e32 v11, v12
	s_waitcnt lgkmcnt(0)
	v_mov_b32_e32 v20, v12
	v_mov_b32_e32 v21, v12
	v_mov_b32_e32 v22, v12
	v_mov_b32_e32 v23, v12
	v_mov_b32_e32 v24, v12
	v_mov_b32_e32 v25, v12
	v_mov_b32_e32 v26, v12
	v_mov_b32_e32 v27, v12
	v_mov_b32_e32 v36, v12
	v_mov_b32_e32 v37, v12
	v_mov_b32_e32 v38, v12
	v_mov_b32_e32 v39, v12
	v_mov_b32_e32 v40, v12
	v_mov_b32_e32 v41, v12
	v_mov_b32_e32 v42, v12
	v_mov_b32_e32 v43, v12
	v_mov_b32_e32 v52, v12
	v_mov_b32_e32 v53, v12
	v_mov_b32_e32 v54, v12
	v_mov_b32_e32 v55, v12
	v_mov_b32_e32 v56, v12
	v_mov_b32_e32 v57, v12
	v_mov_b32_e32 v58, v12
	v_mov_b32_e32 v59, v12
	v_mov_b32_e32 v76, v12
	v_mov_b32_e32 v77, v12
	v_mov_b32_e32 v78, v12
	v_mov_b32_e32 v79, v12
	v_mov_b32_e32 v80, v12
	v_mov_b32_e32 v81, v12
	v_mov_b32_e32 v82, v12
	v_mov_b32_e32 v83, v12
	v_mov_b32_e32 v92, v12
	v_mov_b32_e32 v93, v12
	v_mov_b32_e32 v94, v12
	v_mov_b32_e32 v95, v12
	v_mov_b32_e32 v96, v12
	v_mov_b32_e32 v97, v12
	v_mov_b32_e32 v98, v12
	v_mov_b32_e32 v99, v12
	v_mov_b32_e32 v108, v12
	v_mov_b32_e32 v109, v12
	v_mov_b32_e32 v110, v12
	v_mov_b32_e32 v111, v12
	v_mov_b32_e32 v112, v12
	v_mov_b32_e32 v113, v12
	v_mov_b32_e32 v114, v12
	v_mov_b32_e32 v115, v12
	v_mov_b32_e32 v124, v12
	v_mov_b32_e32 v125, v12
	v_mov_b32_e32 v126, v12
	v_mov_b32_e32 v127, v12
	v_mov_b32_e32 v128, v12
	v_mov_b32_e32 v129, v12
	v_mov_b32_e32 v130, v12
	v_mov_b32_e32 v131, v12
	v_mov_b32_e32 v68, v12
	v_mov_b32_e32 v69, v12
	v_mov_b32_e32 v70, v12
	v_mov_b32_e32 v71, v12
	v_mov_b32_e32 v72, v12
	v_mov_b32_e32 v73, v12
	v_mov_b32_e32 v74, v12
	v_mov_b32_e32 v75, v12
	v_mov_b32_e32 v84, v12
	v_mov_b32_e32 v85, v12
	v_mov_b32_e32 v86, v12
	v_mov_b32_e32 v87, v12
	v_mov_b32_e32 v88, v12
	v_mov_b32_e32 v89, v12
	v_mov_b32_e32 v90, v12
	v_mov_b32_e32 v91, v12
	v_mov_b32_e32 v100, v12
	v_mov_b32_e32 v101, v12
	v_mov_b32_e32 v102, v12
	v_mov_b32_e32 v103, v12
	v_mov_b32_e32 v104, v12
	v_mov_b32_e32 v105, v12
	v_mov_b32_e32 v106, v12
	v_mov_b32_e32 v107, v12
	v_mov_b32_e32 v116, v12
	v_mov_b32_e32 v117, v12
	v_mov_b32_e32 v118, v12
	v_mov_b32_e32 v119, v12
	v_mov_b32_e32 v120, v12
	v_mov_b32_e32 v121, v12
	v_mov_b32_e32 v122, v12
	v_mov_b32_e32 v123, v12

.LBB0_755:
	v_mov_b32_e32 v145, v156
	v_mov_b32_e32 v144, v1
	s_lshl_b32 s55, s16, 8
	v_lshl_add_u32 v146, v145, 4, v144
	v_add_u32_e32 v2, s69, v146
	v_cmp_gt_i32_e32 vcc, s85, v2
	s_and_saveexec_b64 s[16:17], vcc
	s_cbranch_execz .LBB0_757
	v_lshlrev_b32_e32 v164, 6, v2
	v_add_u32_e32 v164, 0x20400, v164
	ds_read_b128 v[148:151], v164
	ds_read_b128 v[152:155], v164 offset:32
	ds_read_b128 v[160:163], v164 offset:16
	ds_read_b128 v[164:167], v164 offset:48
	s_mov_b32 s15, 0x800000
	v_lshl_add_u32 v2, v2, 2, v225
	s_waitcnt lgkmcnt(0)
	v_mov_b32_e32 v168, v148
	v_mov_b32_e32 v169, v152
	v_mov_b32_e32 v152, v149
	v_mov_b32_e32 v148, v150
	v_mov_b32_e32 v149, v154
	v_mov_b32_e32 v154, v151
	v_mov_b32_e32 v150, v160
	v_mov_b32_e32 v151, v164
	v_mov_b32_e32 v164, v161
	v_mov_b32_e32 v160, v162
	v_mov_b32_e32 v161, v166
	v_mov_b32_e32 v166, v163
	v_pk_add_f32 v[152:153], v[168:169], v[152:153]
	v_pk_add_f32 v[148:149], v[148:149], v[154:155]
	v_pk_add_f32 v[150:151], v[150:151], v[164:165]
	v_pk_add_f32 v[154:155], v[160:161], v[166:167]
	v_pk_add_f32 v[148:149], v[152:153], v[148:149]
	v_pk_add_f32 v[150:151], v[150:151], v[154:155]
	s_nop 0
	v_pk_add_f32 v[148:149], v[148:149], v[150:151]
	s_nop 0
	v_add_f32_e32 v147, v148, v149
	v_fmamk_f32 v147, v147, 0x3a800000, v223
	v_mul_f32_e32 v148, 0x4b800000, v147
	v_cmp_gt_f32_e32 vcc, s15, v147
	s_nop 1
	v_cndmask_b32_e32 v147, v147, v148, vcc
	v_rsq_f32_e32 v147, v147
	s_nop 0
	v_mul_f32_e32 v148, 0x45800000, v147
	v_cndmask_b32_e32 v147, v147, v148, vcc
	ds_write_b32 v2, v147
